# attention lazy-rescale test: row-max as two interleaved 8-deep v_max3 chains, reference+8 add in the permlane wait slot, self-max canonicalisations removed (asm guide 7.12)
# baseline (speedup 1.0000x reference)
.LBB0_326:
	v_max3_f32 v191, v114, s66, v115
	v_max3_f32 v220, v116, s66, v117
	v_max3_f32 v191, v191, v118, v119
	v_max3_f32 v220, v220, v120, v121
	v_max3_f32 v191, v191, v122, v123
	v_max3_f32 v220, v220, v124, v125
	v_max3_f32 v191, v191, v126, v127
	v_max3_f32 v220, v220, v128, v129
	s_nop 1
	v_max3_f32 v191, v191, v98, v99
	v_max3_f32 v220, v220, v100, v101
	v_max3_f32 v191, v191, v102, v103
	v_max3_f32 v220, v220, v104, v105
	v_max3_f32 v191, v191, v106, v107
	v_max3_f32 v220, v220, v108, v109
	v_max3_f32 v191, v191, v110, v111
	v_max3_f32 v220, v220, v112, v113
	v_max_f32_e32 v191, v191, v220
	v_mov_b32_e32 v192, v191
	v_add_f32_e32 v221, 0x41000000, v186
	s_nop 0
	v_permlane32_swap_b32_e32 v191, v192
	v_max_f32_e32 v191, v191, v192
	v_cmp_gt_f32_e32 vcc, v191, v221
	s_cbranch_vccz .LBB0_328
	s_nop 0
	v_cndmask_b32_e32 v191, v186, v191, vcc
	v_sub_f32_e32 v186, v186, v191
	v_exp_f32_e32 v186, v186
	s_nop 0
	v_mul_f32_e32 v201, v201, v186
	v_pk_mul_f32 v[64:65], v[64:65], v[186:187] op_sel_hi:[1,0]
	v_pk_mul_f32 v[62:63], v[62:63], v[186:187] op_sel_hi:[1,0]
	v_pk_mul_f32 v[60:61], v[60:61], v[186:187] op_sel_hi:[1,0]
	v_pk_mul_f32 v[58:59], v[58:59], v[186:187] op_sel_hi:[1,0]
	v_pk_mul_f32 v[56:57], v[56:57], v[186:187] op_sel_hi:[1,0]
	v_pk_mul_f32 v[54:55], v[54:55], v[186:187] op_sel_hi:[1,0]
	v_pk_mul_f32 v[52:53], v[52:53], v[186:187] op_sel_hi:[1,0]
	v_pk_mul_f32 v[50:51], v[50:51], v[186:187] op_sel_hi:[1,0]
	v_pk_mul_f32 v[48:49], v[48:49], v[186:187] op_sel_hi:[1,0]
	v_pk_mul_f32 v[46:47], v[46:47], v[186:187] op_sel_hi:[1,0]
	v_pk_mul_f32 v[44:45], v[44:45], v[186:187] op_sel_hi:[1,0]
	v_pk_mul_f32 v[42:43], v[42:43], v[186:187] op_sel_hi:[1,0]
	v_pk_mul_f32 v[40:41], v[40:41], v[186:187] op_sel_hi:[1,0]
	v_pk_mul_f32 v[38:39], v[38:39], v[186:187] op_sel_hi:[1,0]
	v_pk_mul_f32 v[36:37], v[36:37], v[186:187] op_sel_hi:[1,0]
	v_pk_mul_f32 v[34:35], v[34:35], v[186:187] op_sel_hi:[1,0]
	v_mov_b32_e32 v186, v191

.LBB0_330:
	v_max3_f32 v190, v82, s66, v83
	v_max3_f32 v220, v84, s66, v85
	v_max3_f32 v190, v190, v86, v87
	v_max3_f32 v220, v220, v88, v89
	v_max3_f32 v190, v190, v90, v91
	v_max3_f32 v220, v220, v92, v93
	v_max3_f32 v190, v190, v94, v95
	v_max3_f32 v220, v220, v96, v97
	v_max3_f32 v190, v190, v66, v67
	v_max3_f32 v220, v220, v68, v69
	v_max3_f32 v190, v190, v70, v71
	v_max3_f32 v220, v220, v72, v73
	v_max3_f32 v190, v190, v74, v75
	v_max3_f32 v220, v220, v76, v77
	v_max3_f32 v190, v190, v78, v79
	v_max3_f32 v220, v220, v80, v81
	v_max_f32_e32 v190, v190, v220
	v_mov_b32_e32 v191, v190
	v_add_f32_e32 v221, 0x41000000, v188
	s_nop 0
	v_permlane32_swap_b32_e32 v190, v191
	v_max_f32_e32 v190, v190, v191
	v_cmp_gt_f32_e32 vcc, v190, v221
	s_cbranch_vccz .LBB0_319
	s_nop 0
	v_cndmask_b32_e32 v190, v188, v190, vcc
	v_sub_f32_e32 v188, v188, v190
	v_exp_f32_e32 v188, v188
	s_nop 0
	v_mul_f32_e32 v199, v199, v188
	v_pk_mul_f32 v[32:33], v[32:33], v[188:189] op_sel_hi:[1,0]
	v_pk_mul_f32 v[30:31], v[30:31], v[188:189] op_sel_hi:[1,0]
	v_pk_mul_f32 v[28:29], v[28:29], v[188:189] op_sel_hi:[1,0]
	v_pk_mul_f32 v[26:27], v[26:27], v[188:189] op_sel_hi:[1,0]
	v_pk_mul_f32 v[24:25], v[24:25], v[188:189] op_sel_hi:[1,0]
	v_pk_mul_f32 v[22:23], v[22:23], v[188:189] op_sel_hi:[1,0]
	v_pk_mul_f32 v[20:21], v[20:21], v[188:189] op_sel_hi:[1,0]
	v_pk_mul_f32 v[18:19], v[18:19], v[188:189] op_sel_hi:[1,0]
	v_pk_mul_f32 v[16:17], v[16:17], v[188:189] op_sel_hi:[1,0]
	v_pk_mul_f32 v[14:15], v[14:15], v[188:189] op_sel_hi:[1,0]
	v_pk_mul_f32 v[12:13], v[12:13], v[188:189] op_sel_hi:[1,0]
	v_pk_mul_f32 v[10:11], v[10:11], v[188:189] op_sel_hi:[1,0]
	v_pk_mul_f32 v[8:9], v[8:9], v[188:189] op_sel_hi:[1,0]
	v_pk_mul_f32 v[6:7], v[6:7], v[188:189] op_sel_hi:[1,0]
	v_pk_mul_f32 v[4:5], v[4:5], v[188:189] op_sel_hi:[1,0]
	v_pk_mul_f32 v[2:3], v[2:3], v[188:189] op_sel_hi:[1,0]
	v_mov_b32_e32 v188, v190
	s_branch .LBB0_319

.LBB0_385:
	v_max3_f32 v206, v128, s66, v129
	v_max3_f32 v220, v130, s66, v131
	v_max3_f32 v206, v206, v132, v133
	v_max3_f32 v220, v220, v134, v135
	v_max3_f32 v206, v206, v136, v137
	v_max3_f32 v220, v220, v138, v139
	v_max3_f32 v206, v206, v140, v141
	v_max3_f32 v220, v220, v142, v143
	v_max3_f32 v206, v206, v112, v113
	v_max3_f32 v220, v220, v114, v115
	v_max3_f32 v206, v206, v116, v117
	v_max3_f32 v220, v220, v118, v119
	v_max3_f32 v206, v206, v120, v121
	v_max3_f32 v220, v220, v122, v123
	v_max3_f32 v206, v206, v124, v125
	v_max3_f32 v220, v220, v126, v127
	v_max_f32_e32 v206, v206, v220
	v_mov_b32_e32 v207, v206
	v_add_f32_e32 v221, 0x41000000, v200
	s_nop 0
	v_permlane32_swap_b32_e32 v206, v207
	v_max_f32_e32 v206, v206, v207
	v_cmp_gt_f32_e32 vcc, v206, v221
	s_cbranch_vccz .LBB0_387
	s_nop 0
	v_cndmask_b32_e32 v206, v200, v206, vcc
	v_sub_f32_e32 v200, v200, v206
	v_exp_f32_e32 v200, v200
	s_nop 0
	v_mul_f32_e32 v216, v216, v200
	v_pk_mul_f32 v[78:79], v[78:79], v[200:201] op_sel_hi:[1,0]
	v_pk_mul_f32 v[76:77], v[76:77], v[200:201] op_sel_hi:[1,0]
	v_pk_mul_f32 v[74:75], v[74:75], v[200:201] op_sel_hi:[1,0]
	v_pk_mul_f32 v[72:73], v[72:73], v[200:201] op_sel_hi:[1,0]
	v_pk_mul_f32 v[70:71], v[70:71], v[200:201] op_sel_hi:[1,0]
	v_pk_mul_f32 v[68:69], v[68:69], v[200:201] op_sel_hi:[1,0]
	v_pk_mul_f32 v[66:67], v[66:67], v[200:201] op_sel_hi:[1,0]
	v_pk_mul_f32 v[64:65], v[64:65], v[200:201] op_sel_hi:[1,0]
	v_pk_mul_f32 v[62:63], v[62:63], v[200:201] op_sel_hi:[1,0]
	v_pk_mul_f32 v[60:61], v[60:61], v[200:201] op_sel_hi:[1,0]
	v_pk_mul_f32 v[58:59], v[58:59], v[200:201] op_sel_hi:[1,0]
	v_pk_mul_f32 v[56:57], v[56:57], v[200:201] op_sel_hi:[1,0]
	v_pk_mul_f32 v[54:55], v[54:55], v[200:201] op_sel_hi:[1,0]
	v_pk_mul_f32 v[52:53], v[52:53], v[200:201] op_sel_hi:[1,0]
	v_pk_mul_f32 v[50:51], v[50:51], v[200:201] op_sel_hi:[1,0]
	v_pk_mul_f32 v[48:49], v[48:49], v[200:201] op_sel_hi:[1,0]
	v_mov_b32_e32 v200, v206

.LBB0_389:
	v_max3_f32 v2, v80, s66, v81
	v_max3_f32 v220, v82, s66, v83
	v_max3_f32 v2, v2, v84, v85
	v_max3_f32 v220, v220, v86, v87
	v_max3_f32 v2, v2, v88, v89
	v_max3_f32 v220, v220, v90, v91
	v_max3_f32 v2, v2, v92, v93
	v_max3_f32 v220, v220, v94, v95
	v_max3_f32 v2, v2, v96, v97
	v_max3_f32 v220, v220, v98, v99
	v_max3_f32 v2, v2, v100, v101
	v_max3_f32 v220, v220, v102, v103
	v_max3_f32 v2, v2, v104, v105
	v_max3_f32 v220, v220, v106, v107
	v_max3_f32 v2, v2, v108, v109
	v_max3_f32 v220, v220, v110, v111
	v_max_f32_e32 v2, v2, v220
	v_mov_b32_e32 v3, v2
	v_add_f32_e32 v221, 0x41000000, v202
	s_nop 0
	v_permlane32_swap_b32_e32 v2, v3
	v_max_f32_e32 v2, v2, v3
	v_cmp_gt_f32_e32 vcc, v2, v221
	s_cbranch_vccz .LBB0_378
	s_nop 0
	v_cndmask_b32_e32 v3, v202, v2, vcc
	v_sub_f32_e32 v2, v202, v3
	v_exp_f32_e32 v2, v2
	v_mov_b32_e32 v202, v3
	v_mul_f32_e32 v212, v212, v2
	v_pk_mul_f32 v[46:47], v[46:47], v[2:3] op_sel_hi:[1,0]
	v_pk_mul_f32 v[44:45], v[44:45], v[2:3] op_sel_hi:[1,0]
	v_pk_mul_f32 v[42:43], v[42:43], v[2:3] op_sel_hi:[1,0]
	v_pk_mul_f32 v[40:41], v[40:41], v[2:3] op_sel_hi:[1,0]
	v_pk_mul_f32 v[38:39], v[38:39], v[2:3] op_sel_hi:[1,0]
	v_pk_mul_f32 v[36:37], v[36:37], v[2:3] op_sel_hi:[1,0]
	v_pk_mul_f32 v[34:35], v[34:35], v[2:3] op_sel_hi:[1,0]
	v_pk_mul_f32 v[32:33], v[32:33], v[2:3] op_sel_hi:[1,0]
	v_pk_mul_f32 v[30:31], v[30:31], v[2:3] op_sel_hi:[1,0]
	v_pk_mul_f32 v[28:29], v[28:29], v[2:3] op_sel_hi:[1,0]
	v_pk_mul_f32 v[26:27], v[26:27], v[2:3] op_sel_hi:[1,0]
	v_pk_mul_f32 v[24:25], v[24:25], v[2:3] op_sel_hi:[1,0]
	v_pk_mul_f32 v[22:23], v[22:23], v[2:3] op_sel_hi:[1,0]
	v_pk_mul_f32 v[20:21], v[20:21], v[2:3] op_sel_hi:[1,0]
	v_pk_mul_f32 v[18:19], v[18:19], v[2:3] op_sel_hi:[1,0]
	v_pk_mul_f32 v[16:17], v[16:17], v[2:3] op_sel_hi:[1,0]
	s_branch .LBB0_378
